# passC carry-fold: load ladder de-serialised (16 steps of SUMM loads issued together, one wait, then the fmac chain); on top of Gray MFMA order
# speedup vs baseline: 1.0003x; 1.0003x over previous
.LBB0_464:
	s_and_b64 s[18:19], exec, s[16:17]
	s_cselect_b32 s35, 3, 63
	s_and_b32 s1, s35, s4
	s_cmp_eq_u32 s1, 0
	s_cselect_b64 s[18:19], -1, 0
	s_and_b64 vcc, exec, s[18:19]
	s_cbranch_vccnz .LBB0_471
	s_ashr_i32 s5, s4, 31
	s_lshl_b64 s[22:23], s[4:5], 13
	s_cmp_lt_u32 s1, 16
	s_mov_b32 s20, 0
	s_cbranch_scc1 .LBB0_468
	s_lshl_b32 s5, s1, 13
	s_sub_u32 s24, s22, s5
	s_subb_u32 s25, s23, 0
	v_lshl_add_u64 v[64:65], v[100:101], 0, s[24:25]
	s_and_b32 s5, s5, 0x60000
	s_mov_b64 s[24:25], 0
	s_mov_b64 s[98:99], 0x2000
.LBB0_467:
	v_lshl_add_u64 v[68:69], v[64:65], 0, s[24:25]
	global_load_dword v152, v[68:69], off
	global_load_dword v168, v[68:69], off offset:2048
	v_lshl_add_u64 v[68:69], v[68:69], 0, s[98:99]
	global_load_dword v153, v[68:69], off
	global_load_dword v169, v[68:69], off offset:2048
	v_lshl_add_u64 v[68:69], v[68:69], 0, s[98:99]
	global_load_dword v154, v[68:69], off
	global_load_dword v170, v[68:69], off offset:2048
	v_lshl_add_u64 v[68:69], v[68:69], 0, s[98:99]
	global_load_dword v155, v[68:69], off
	global_load_dword v171, v[68:69], off offset:2048
	v_lshl_add_u64 v[68:69], v[68:69], 0, s[98:99]
	global_load_dword v156, v[68:69], off
	global_load_dword v172, v[68:69], off offset:2048
	v_lshl_add_u64 v[68:69], v[68:69], 0, s[98:99]
	global_load_dword v157, v[68:69], off
	global_load_dword v173, v[68:69], off offset:2048
	v_lshl_add_u64 v[68:69], v[68:69], 0, s[98:99]
	global_load_dword v158, v[68:69], off
	global_load_dword v174, v[68:69], off offset:2048
	v_lshl_add_u64 v[68:69], v[68:69], 0, s[98:99]
	global_load_dword v159, v[68:69], off
	global_load_dword v175, v[68:69], off offset:2048
	v_lshl_add_u64 v[68:69], v[68:69], 0, s[98:99]
	global_load_dword v160, v[68:69], off
	global_load_dword v176, v[68:69], off offset:2048
	v_lshl_add_u64 v[68:69], v[68:69], 0, s[98:99]
	global_load_dword v161, v[68:69], off
	global_load_dword v177, v[68:69], off offset:2048
	v_lshl_add_u64 v[68:69], v[68:69], 0, s[98:99]
	global_load_dword v162, v[68:69], off
	global_load_dword v178, v[68:69], off offset:2048
	v_lshl_add_u64 v[68:69], v[68:69], 0, s[98:99]
	global_load_dword v163, v[68:69], off
	global_load_dword v179, v[68:69], off offset:2048
	v_lshl_add_u64 v[68:69], v[68:69], 0, s[98:99]
	global_load_dword v164, v[68:69], off
	global_load_dword v180, v[68:69], off offset:2048
	v_lshl_add_u64 v[68:69], v[68:69], 0, s[98:99]
	global_load_dword v165, v[68:69], off
	global_load_dword v181, v[68:69], off offset:2048
	v_lshl_add_u64 v[68:69], v[68:69], 0, s[98:99]
	global_load_dword v166, v[68:69], off
	global_load_dword v182, v[68:69], off offset:2048
	v_lshl_add_u64 v[68:69], v[68:69], 0, s[98:99]
	global_load_dword v167, v[68:69], off
	global_load_dword v183, v[68:69], off offset:2048
	s_add_i32 s20, s20, 16
	s_add_u32 s24, s24, 0x20000
	s_addc_u32 s25, s25, 0
	s_waitcnt vmcnt(0)
	v_fmac_f32_e32 v168, v136, v152
	v_fmac_f32_e32 v169, v168, v153
	v_fmac_f32_e32 v170, v169, v154
	v_fmac_f32_e32 v171, v170, v155
	v_fmac_f32_e32 v172, v171, v156
	v_fmac_f32_e32 v173, v172, v157
	v_fmac_f32_e32 v174, v173, v158
	v_fmac_f32_e32 v175, v174, v159
	v_fmac_f32_e32 v176, v175, v160
	v_fmac_f32_e32 v177, v176, v161
	v_fmac_f32_e32 v178, v177, v162
	v_fmac_f32_e32 v179, v178, v163
	v_fmac_f32_e32 v180, v179, v164
	v_fmac_f32_e32 v181, v180, v165
	v_fmac_f32_e32 v182, v181, v166
	v_fmac_f32_e32 v183, v182, v167
	v_mov_b32_e32 v136, v183
	s_cmp_eq_u32 s5, s24
	s_cbranch_scc0 .LBB0_467
.LBB0_468:
	s_and_b32 s5, s1, 15
	s_cmp_eq_u32 s5, 0
	s_cbranch_scc1 .LBB0_471
	s_lshl_b64 s[24:25], s[20:21], 13
	s_add_u32 s20, s22, s24
	s_addc_u32 s23, s23, s25
	s_lshl_b32 s22, s1, 13
	s_sub_u32 s22, s20, s22
	s_subb_u32 s23, s23, 0
	v_lshl_add_u64 v[64:65], v[104:105], 0, s[22:23]
	s_mov_b64 s[98:99], 0x2000
	v_mov_b32_e32 v68, v64
	v_mov_b32_e32 v69, v65
	global_load_dword v168, v[68:69], off
	global_load_dword v152, v[68:69], off offset:-2048
	v_lshl_add_u64 v[68:69], v[68:69], 0, s[98:99]
	global_load_dword v169, v[68:69], off
	global_load_dword v153, v[68:69], off offset:-2048
	v_lshl_add_u64 v[68:69], v[68:69], 0, s[98:99]
	global_load_dword v170, v[68:69], off
	global_load_dword v154, v[68:69], off offset:-2048
	v_lshl_add_u64 v[68:69], v[68:69], 0, s[98:99]
	global_load_dword v171, v[68:69], off
	global_load_dword v155, v[68:69], off offset:-2048
	v_lshl_add_u64 v[68:69], v[68:69], 0, s[98:99]
	global_load_dword v172, v[68:69], off
	global_load_dword v156, v[68:69], off offset:-2048
	v_lshl_add_u64 v[68:69], v[68:69], 0, s[98:99]
	global_load_dword v173, v[68:69], off
	global_load_dword v157, v[68:69], off offset:-2048
	v_lshl_add_u64 v[68:69], v[68:69], 0, s[98:99]
	global_load_dword v174, v[68:69], off
	global_load_dword v158, v[68:69], off offset:-2048
	v_lshl_add_u64 v[68:69], v[68:69], 0, s[98:99]
	global_load_dword v175, v[68:69], off
	global_load_dword v159, v[68:69], off offset:-2048
	v_lshl_add_u64 v[68:69], v[68:69], 0, s[98:99]
	global_load_dword v176, v[68:69], off
	global_load_dword v160, v[68:69], off offset:-2048
	v_lshl_add_u64 v[68:69], v[68:69], 0, s[98:99]
	global_load_dword v177, v[68:69], off
	global_load_dword v161, v[68:69], off offset:-2048
	v_lshl_add_u64 v[68:69], v[68:69], 0, s[98:99]
	global_load_dword v178, v[68:69], off
	global_load_dword v162, v[68:69], off offset:-2048
	v_lshl_add_u64 v[68:69], v[68:69], 0, s[98:99]
	global_load_dword v179, v[68:69], off
	global_load_dword v163, v[68:69], off offset:-2048
	v_lshl_add_u64 v[68:69], v[68:69], 0, s[98:99]
	global_load_dword v180, v[68:69], off
	global_load_dword v164, v[68:69], off offset:-2048
	v_lshl_add_u64 v[68:69], v[68:69], 0, s[98:99]
	global_load_dword v181, v[68:69], off
	global_load_dword v165, v[68:69], off offset:-2048
	v_lshl_add_u64 v[68:69], v[68:69], 0, s[98:99]
	global_load_dword v182, v[68:69], off
	global_load_dword v166, v[68:69], off offset:-2048
	s_waitcnt vmcnt(0)
	v_fmac_f32_e32 v168, v136, v152
	v_mov_b32_e32 v136, v168
	s_cmp_eq_u32 s5, 1
	s_cbranch_scc1 .Lcf_fwd_done
	v_fmac_f32_e32 v169, v136, v153
	v_mov_b32_e32 v136, v169
	s_cmp_eq_u32 s5, 2
	s_cbranch_scc1 .Lcf_fwd_done
	v_fmac_f32_e32 v170, v136, v154
	v_mov_b32_e32 v136, v170
	s_cmp_eq_u32 s5, 3
	s_cbranch_scc1 .Lcf_fwd_done
	v_fmac_f32_e32 v171, v136, v155
	v_mov_b32_e32 v136, v171
	s_cmp_eq_u32 s5, 4
	s_cbranch_scc1 .Lcf_fwd_done
	v_fmac_f32_e32 v172, v136, v156
	v_mov_b32_e32 v136, v172
	s_cmp_eq_u32 s5, 5
	s_cbranch_scc1 .Lcf_fwd_done
	v_fmac_f32_e32 v173, v136, v157
	v_mov_b32_e32 v136, v173
	s_cmp_eq_u32 s5, 6
	s_cbranch_scc1 .Lcf_fwd_done
	v_fmac_f32_e32 v174, v136, v158
	v_mov_b32_e32 v136, v174
	s_cmp_eq_u32 s5, 7
	s_cbranch_scc1 .Lcf_fwd_done
	v_fmac_f32_e32 v175, v136, v159
	v_mov_b32_e32 v136, v175
	s_cmp_eq_u32 s5, 8
	s_cbranch_scc1 .Lcf_fwd_done
	v_fmac_f32_e32 v176, v136, v160
	v_mov_b32_e32 v136, v176
	s_cmp_eq_u32 s5, 9
	s_cbranch_scc1 .Lcf_fwd_done
	v_fmac_f32_e32 v177, v136, v161
	v_mov_b32_e32 v136, v177
	s_cmp_eq_u32 s5, 10
	s_cbranch_scc1 .Lcf_fwd_done
	v_fmac_f32_e32 v178, v136, v162
	v_mov_b32_e32 v136, v178
	s_cmp_eq_u32 s5, 11
	s_cbranch_scc1 .Lcf_fwd_done
	v_fmac_f32_e32 v179, v136, v163
	v_mov_b32_e32 v136, v179
	s_cmp_eq_u32 s5, 12
	s_cbranch_scc1 .Lcf_fwd_done
	v_fmac_f32_e32 v180, v136, v164
	v_mov_b32_e32 v136, v180
	s_cmp_eq_u32 s5, 13
	s_cbranch_scc1 .Lcf_fwd_done
	v_fmac_f32_e32 v181, v136, v165
	v_mov_b32_e32 v136, v181
	s_cmp_eq_u32 s5, 14
	s_cbranch_scc1 .Lcf_fwd_done
	v_fmac_f32_e32 v182, v136, v166
	v_mov_b32_e32 v136, v182
.Lcf_fwd_done:
.LBB0_471:
	s_cmp_eq_u32 s1, s35
	s_cselect_b64 s[22:23], -1, 0
	s_and_b64 vcc, exec, s[22:23]
	s_cbranch_vccnz .LBB0_477
	s_add_i32 s5, s35, -1
	s_sub_i32 s24, s4, s1
	s_min_u32 s5, s1, s5
	s_ashr_i32 s25, s24, 31
	s_sub_i32 s20, s35, s5
	s_lshl_b64 s[24:25], s[24:25], 13
	s_and_b32 s20, s20, 15
	v_lshl_add_u64 v[64:65], v[102:103], 0, s[24:25]
	s_cmp_eq_u32 s20, 0
	s_cbranch_scc1 .LBB0_481
	s_mov_b32 s100, s20
	s_sub_i32 s24, s35, s20
	s_mov_b32 s20, s35
	s_lshl_b64 s[38:39], s[20:21], 13
	s_add_u32 s38, s38, 0x1000
	s_addc_u32 s39, s39, 0
	v_lshl_add_u64 v[68:69], v[64:65], 0, s[38:39]
	s_mov_b32 s98, 0xffffe000
	s_mov_b32 s99, -1
	global_load_dword v152, v[68:69], off
	global_load_dword v168, v[68:69], off offset:2048
	v_lshl_add_u64 v[68:69], v[68:69], 0, s[98:99]
	global_load_dword v153, v[68:69], off
	global_load_dword v169, v[68:69], off offset:2048
	v_lshl_add_u64 v[68:69], v[68:69], 0, s[98:99]
	global_load_dword v154, v[68:69], off
	global_load_dword v170, v[68:69], off offset:2048
	v_lshl_add_u64 v[68:69], v[68:69], 0, s[98:99]
	global_load_dword v155, v[68:69], off
	global_load_dword v171, v[68:69], off offset:2048
	v_lshl_add_u64 v[68:69], v[68:69], 0, s[98:99]
	global_load_dword v156, v[68:69], off
	global_load_dword v172, v[68:69], off offset:2048
	v_lshl_add_u64 v[68:69], v[68:69], 0, s[98:99]
	global_load_dword v157, v[68:69], off
	global_load_dword v173, v[68:69], off offset:2048
	v_lshl_add_u64 v[68:69], v[68:69], 0, s[98:99]
	global_load_dword v158, v[68:69], off
	global_load_dword v174, v[68:69], off offset:2048
	v_lshl_add_u64 v[68:69], v[68:69], 0, s[98:99]
	global_load_dword v159, v[68:69], off
	global_load_dword v175, v[68:69], off offset:2048
	v_lshl_add_u64 v[68:69], v[68:69], 0, s[98:99]
	global_load_dword v160, v[68:69], off
	global_load_dword v176, v[68:69], off offset:2048
	v_lshl_add_u64 v[68:69], v[68:69], 0, s[98:99]
	global_load_dword v161, v[68:69], off
	global_load_dword v177, v[68:69], off offset:2048
	v_lshl_add_u64 v[68:69], v[68:69], 0, s[98:99]
	global_load_dword v162, v[68:69], off
	global_load_dword v178, v[68:69], off offset:2048
	v_lshl_add_u64 v[68:69], v[68:69], 0, s[98:99]
	global_load_dword v163, v[68:69], off
	global_load_dword v179, v[68:69], off offset:2048
	v_lshl_add_u64 v[68:69], v[68:69], 0, s[98:99]
	global_load_dword v164, v[68:69], off
	global_load_dword v180, v[68:69], off offset:2048
	v_lshl_add_u64 v[68:69], v[68:69], 0, s[98:99]
	global_load_dword v165, v[68:69], off
	global_load_dword v181, v[68:69], off offset:2048
	v_lshl_add_u64 v[68:69], v[68:69], 0, s[98:99]
	global_load_dword v166, v[68:69], off
	global_load_dword v182, v[68:69], off offset:2048
	s_waitcnt vmcnt(0)
	v_fmac_f32_e32 v168, v97, v152
	v_mov_b32_e32 v97, v168
	s_cmp_eq_u32 s100, 1
	s_cbranch_scc1 .Lcf_bwd_done
	v_fmac_f32_e32 v169, v97, v153
	v_mov_b32_e32 v97, v169
	s_cmp_eq_u32 s100, 2
	s_cbranch_scc1 .Lcf_bwd_done
	v_fmac_f32_e32 v170, v97, v154
	v_mov_b32_e32 v97, v170
	s_cmp_eq_u32 s100, 3
	s_cbranch_scc1 .Lcf_bwd_done
	v_fmac_f32_e32 v171, v97, v155
	v_mov_b32_e32 v97, v171
	s_cmp_eq_u32 s100, 4
	s_cbranch_scc1 .Lcf_bwd_done
	v_fmac_f32_e32 v172, v97, v156
	v_mov_b32_e32 v97, v172
	s_cmp_eq_u32 s100, 5
	s_cbranch_scc1 .Lcf_bwd_done
	v_fmac_f32_e32 v173, v97, v157
	v_mov_b32_e32 v97, v173
	s_cmp_eq_u32 s100, 6
	s_cbranch_scc1 .Lcf_bwd_done
	v_fmac_f32_e32 v174, v97, v158
	v_mov_b32_e32 v97, v174
	s_cmp_eq_u32 s100, 7
	s_cbranch_scc1 .Lcf_bwd_done
	v_fmac_f32_e32 v175, v97, v159
	v_mov_b32_e32 v97, v175
	s_cmp_eq_u32 s100, 8
	s_cbranch_scc1 .Lcf_bwd_done
	v_fmac_f32_e32 v176, v97, v160
	v_mov_b32_e32 v97, v176
	s_cmp_eq_u32 s100, 9
	s_cbranch_scc1 .Lcf_bwd_done
	v_fmac_f32_e32 v177, v97, v161
	v_mov_b32_e32 v97, v177
	s_cmp_eq_u32 s100, 10
	s_cbranch_scc1 .Lcf_bwd_done
	v_fmac_f32_e32 v178, v97, v162
	v_mov_b32_e32 v97, v178
	s_cmp_eq_u32 s100, 11
	s_cbranch_scc1 .Lcf_bwd_done
	v_fmac_f32_e32 v179, v97, v163
	v_mov_b32_e32 v97, v179
	s_cmp_eq_u32 s100, 12
	s_cbranch_scc1 .Lcf_bwd_done
	v_fmac_f32_e32 v180, v97, v164
	v_mov_b32_e32 v97, v180
	s_cmp_eq_u32 s100, 13
	s_cbranch_scc1 .Lcf_bwd_done
	v_fmac_f32_e32 v181, v97, v165
	v_mov_b32_e32 v97, v181
	s_cmp_eq_u32 s100, 14
	s_cbranch_scc1 .Lcf_bwd_done
	v_fmac_f32_e32 v182, v97, v166
	v_mov_b32_e32 v97, v182
.Lcf_bwd_done:
	v_readlane_b32 s38, v250, 26
	s_mov_b32 s20, s24
	v_readlane_b32 s39, v250, 27
	s_sub_i32 s5, s5, s35
	s_cmp_gt_u32 s5, -16
	s_cbranch_scc1 .LBB0_477
.LBB0_476:
	s_lshl_b64 s[24:25], s[20:21], 13
	s_add_u32 s24, s24, 0x1000
	s_addc_u32 s25, s25, 0
	v_lshl_add_u64 v[68:69], v[64:65], 0, s[24:25]
	s_mov_b32 s98, 0xffffe000
	s_mov_b32 s99, -1
	global_load_dword v152, v[68:69], off
	global_load_dword v168, v[68:69], off offset:2048
	v_lshl_add_u64 v[68:69], v[68:69], 0, s[98:99]
	global_load_dword v153, v[68:69], off
	global_load_dword v169, v[68:69], off offset:2048
	v_lshl_add_u64 v[68:69], v[68:69], 0, s[98:99]
	global_load_dword v154, v[68:69], off
	global_load_dword v170, v[68:69], off offset:2048
	v_lshl_add_u64 v[68:69], v[68:69], 0, s[98:99]
	global_load_dword v155, v[68:69], off
	global_load_dword v171, v[68:69], off offset:2048
	v_lshl_add_u64 v[68:69], v[68:69], 0, s[98:99]
	global_load_dword v156, v[68:69], off
	global_load_dword v172, v[68:69], off offset:2048
	v_lshl_add_u64 v[68:69], v[68:69], 0, s[98:99]
	global_load_dword v157, v[68:69], off
	global_load_dword v173, v[68:69], off offset:2048
	v_lshl_add_u64 v[68:69], v[68:69], 0, s[98:99]
	global_load_dword v158, v[68:69], off
	global_load_dword v174, v[68:69], off offset:2048
	v_lshl_add_u64 v[68:69], v[68:69], 0, s[98:99]
	global_load_dword v159, v[68:69], off
	global_load_dword v175, v[68:69], off offset:2048
	v_lshl_add_u64 v[68:69], v[68:69], 0, s[98:99]
	global_load_dword v160, v[68:69], off
	global_load_dword v176, v[68:69], off offset:2048
	v_lshl_add_u64 v[68:69], v[68:69], 0, s[98:99]
	global_load_dword v161, v[68:69], off
	global_load_dword v177, v[68:69], off offset:2048
	v_lshl_add_u64 v[68:69], v[68:69], 0, s[98:99]
	global_load_dword v162, v[68:69], off
	global_load_dword v178, v[68:69], off offset:2048
	v_lshl_add_u64 v[68:69], v[68:69], 0, s[98:99]
	global_load_dword v163, v[68:69], off
	global_load_dword v179, v[68:69], off offset:2048
	v_lshl_add_u64 v[68:69], v[68:69], 0, s[98:99]
	global_load_dword v164, v[68:69], off
	global_load_dword v180, v[68:69], off offset:2048
	v_lshl_add_u64 v[68:69], v[68:69], 0, s[98:99]
	global_load_dword v165, v[68:69], off
	global_load_dword v181, v[68:69], off offset:2048
	v_lshl_add_u64 v[68:69], v[68:69], 0, s[98:99]
	global_load_dword v166, v[68:69], off
	global_load_dword v182, v[68:69], off offset:2048
	v_lshl_add_u64 v[68:69], v[68:69], 0, s[98:99]
	global_load_dword v167, v[68:69], off
	global_load_dword v183, v[68:69], off offset:2048
	s_add_i32 s20, s20, -16
	s_waitcnt vmcnt(0)
	v_fmac_f32_e32 v168, v97, v152
	v_fmac_f32_e32 v169, v168, v153
	v_fmac_f32_e32 v170, v169, v154
	v_fmac_f32_e32 v171, v170, v155
	v_fmac_f32_e32 v172, v171, v156
	v_fmac_f32_e32 v173, v172, v157
	v_fmac_f32_e32 v174, v173, v158
	v_fmac_f32_e32 v175, v174, v159
	v_fmac_f32_e32 v176, v175, v160
	v_fmac_f32_e32 v177, v176, v161
	v_fmac_f32_e32 v178, v177, v162
	v_fmac_f32_e32 v179, v178, v163
	v_fmac_f32_e32 v180, v179, v164
	v_fmac_f32_e32 v181, v180, v165
	v_fmac_f32_e32 v182, v181, v166
	v_fmac_f32_e32 v183, v182, v167
	v_mov_b32_e32 v97, v183
	s_cmp_le_u32 s20, s1
	s_cbranch_scc0 .LBB0_476

	.amdhsa_kernel _Z14fwd_megakernel6Params
		.amdhsa_group_segment_fixed_size 0
		.amdhsa_private_segment_fixed_size 0
		.amdhsa_kernarg_size 480
		.amdhsa_user_sgpr_count 2
		.amdhsa_user_sgpr_dispatch_ptr 0
		.amdhsa_user_sgpr_queue_ptr 0
		.amdhsa_user_sgpr_kernarg_segment_ptr 1
		.amdhsa_user_sgpr_dispatch_id 0
		.amdhsa_user_sgpr_kernarg_preload_length 0
		.amdhsa_user_sgpr_kernarg_preload_offset 0
		.amdhsa_user_sgpr_private_segment_size 0
		.amdhsa_uses_dynamic_stack 0
		.amdhsa_enable_private_segment 0
		.amdhsa_system_sgpr_workgroup_id_x 1
		.amdhsa_system_sgpr_workgroup_id_y 0
		.amdhsa_system_sgpr_workgroup_id_z 0
		.amdhsa_system_sgpr_workgroup_info 0
		.amdhsa_system_vgpr_workitem_id 2
		.amdhsa_next_free_vgpr 252
		.amdhsa_next_free_sgpr 102
		.amdhsa_accum_offset 252
		.amdhsa_reserve_vcc 1
		.amdhsa_float_round_mode_32 0
		.amdhsa_float_round_mode_16_64 0
		.amdhsa_float_denorm_mode_32 3
		.amdhsa_float_denorm_mode_16_64 3
		.amdhsa_dx10_clamp 1
		.amdhsa_ieee_mode 1
		.amdhsa_fp16_overflow 0
		.amdhsa_tg_split 0
		.amdhsa_exception_fp_ieee_invalid_op 0
		.amdhsa_exception_fp_denorm_src 0
		.amdhsa_exception_fp_ieee_div_zero 0
		.amdhsa_exception_fp_ieee_overflow 0
		.amdhsa_exception_fp_ieee_underflow 0
		.amdhsa_exception_fp_ieee_inexact 0
		.amdhsa_exception_int_div_zero 0
	.end_amdhsa_kernel

amdhsa.kernels:
  - .agpr_count:     0
    .args:
      - .offset:         0
        .size:           224
        .value_kind:     by_value
      - .offset:         224
        .size:           4
        .value_kind:     hidden_block_count_x
      - .offset:         228
        .size:           4
        .value_kind:     hidden_block_count_y
      - .offset:         232
        .size:           4
        .value_kind:     hidden_block_count_z
      - .offset:         236
        .size:           2
        .value_kind:     hidden_group_size_x
      - .offset:         238
        .size:           2
        .value_kind:     hidden_group_size_y
      - .offset:         240
        .size:           2
        .value_kind:     hidden_group_size_z
      - .offset:         242
        .size:           2
        .value_kind:     hidden_remainder_x
      - .offset:         244
        .size:           2
        .value_kind:     hidden_remainder_y
      - .offset:         246
        .size:           2
        .value_kind:     hidden_remainder_z
      - .offset:         264
        .size:           8
        .value_kind:     hidden_global_offset_x
      - .offset:         272
        .size:           8
        .value_kind:     hidden_global_offset_y
      - .offset:         280
        .size:           8
        .value_kind:     hidden_global_offset_z
      - .offset:         288
        .size:           2
        .value_kind:     hidden_grid_dims
      - .offset:         312
        .size:           8
        .value_kind:     hidden_multigrid_sync_arg
      - .offset:         344
        .size:           4
        .value_kind:     hidden_dynamic_lds_size
    .group_segment_fixed_size: 0
    .kernarg_segment_align: 8
    .kernarg_segment_size: 480
    .language:       OpenCL C
    .language_version:
      - 2
      - 0
    .max_flat_workgroup_size: 512
    .name:           _Z14fwd_megakernel6Params
    .private_segment_fixed_size: 0
    .sgpr_count:     108
    .sgpr_spill_count: 106
    .symbol:         _Z14fwd_megakernel6Params.kd
    .uniform_work_group_size: 1
    .uses_dynamic_stack: false
    .vgpr_count:     252
    .vgpr_spill_count: 0
    .wavefront_size: 64
